# stack: GEMM setprio flips deleted + P3 w2 loop in 4 batches of 64 loads + first K-fragment ds_reads hoisted to top of each attention step (all bit-identical)
# speedup vs baseline: 1.0046x; 1.0046x over previous
.LBB0_584:
	v_lshl_add_u64 v[158:159], v[8:9], 0, s[16:17]
	global_load_dword v94, v[158:159], off
	global_load_dword v95, v[158:159], off offset:512
	global_load_dword v96, v[158:159], off offset:1024
	global_load_dword v97, v[158:159], off offset:1536
	global_load_dword v98, v[158:159], off offset:2048
	global_load_dword v99, v[158:159], off offset:2560
	global_load_dword v100, v[158:159], off offset:3072
	global_load_dword v101, v[158:159], off offset:3584
	v_add_co_u32_e32 v158, vcc, s21, v158
	s_nop 1
	v_addc_co_u32_e32 v159, vcc, 0, v159, vcc
	global_load_dword v102, v[158:159], off
	global_load_dword v103, v[158:159], off offset:512
	global_load_dword v104, v[158:159], off offset:1024
	global_load_dword v105, v[158:159], off offset:1536
	global_load_dword v106, v[158:159], off offset:2048
	global_load_dword v107, v[158:159], off offset:2560
	global_load_dword v108, v[158:159], off offset:3072
	global_load_dword v109, v[158:159], off offset:3584
	v_add_co_u32_e32 v158, vcc, s21, v158
	s_nop 1
	v_addc_co_u32_e32 v159, vcc, 0, v159, vcc
	global_load_dword v110, v[158:159], off
	global_load_dword v111, v[158:159], off offset:512
	global_load_dword v112, v[158:159], off offset:1024
	global_load_dword v113, v[158:159], off offset:1536
	global_load_dword v114, v[158:159], off offset:2048
	global_load_dword v115, v[158:159], off offset:2560
	global_load_dword v116, v[158:159], off offset:3072
	global_load_dword v117, v[158:159], off offset:3584
	v_add_co_u32_e32 v158, vcc, s21, v158
	s_nop 1
	v_addc_co_u32_e32 v159, vcc, 0, v159, vcc
	global_load_dword v118, v[158:159], off
	global_load_dword v119, v[158:159], off offset:512
	global_load_dword v120, v[158:159], off offset:1024
	global_load_dword v121, v[158:159], off offset:1536
	global_load_dword v122, v[158:159], off offset:2048
	global_load_dword v123, v[158:159], off offset:2560
	global_load_dword v124, v[158:159], off offset:3072
	global_load_dword v125, v[158:159], off offset:3584
	v_add_co_u32_e32 v158, vcc, s21, v158
	s_nop 1
	v_addc_co_u32_e32 v159, vcc, 0, v159, vcc
	global_load_dword v126, v[158:159], off
	global_load_dword v127, v[158:159], off offset:512
	global_load_dword v128, v[158:159], off offset:1024
	global_load_dword v129, v[158:159], off offset:1536
	global_load_dword v130, v[158:159], off offset:2048
	global_load_dword v131, v[158:159], off offset:2560
	global_load_dword v132, v[158:159], off offset:3072
	global_load_dword v133, v[158:159], off offset:3584
	v_add_co_u32_e32 v158, vcc, s21, v158
	s_nop 1
	v_addc_co_u32_e32 v159, vcc, 0, v159, vcc
	global_load_dword v134, v[158:159], off
	global_load_dword v135, v[158:159], off offset:512
	global_load_dword v136, v[158:159], off offset:1024
	global_load_dword v137, v[158:159], off offset:1536
	global_load_dword v138, v[158:159], off offset:2048
	global_load_dword v139, v[158:159], off offset:2560
	global_load_dword v140, v[158:159], off offset:3072
	global_load_dword v141, v[158:159], off offset:3584
	v_add_co_u32_e32 v158, vcc, s21, v158
	s_nop 1
	v_addc_co_u32_e32 v159, vcc, 0, v159, vcc
	global_load_dword v142, v[158:159], off
	global_load_dword v143, v[158:159], off offset:512
	global_load_dword v144, v[158:159], off offset:1024
	global_load_dword v145, v[158:159], off offset:1536
	global_load_dword v146, v[158:159], off offset:2048
	global_load_dword v147, v[158:159], off offset:2560
	global_load_dword v148, v[158:159], off offset:3072
	global_load_dword v149, v[158:159], off offset:3584
	v_add_co_u32_e32 v158, vcc, s21, v158
	s_nop 1
	v_addc_co_u32_e32 v159, vcc, 0, v159, vcc
	global_load_dword v150, v[158:159], off
	global_load_dword v151, v[158:159], off offset:512
	global_load_dword v152, v[158:159], off offset:1024
	global_load_dword v153, v[158:159], off offset:1536
	s_add_u32 s16, s16, 0x8000
	s_addc_u32 s17, s17, 0
	s_cmp_eq_u32 s16, 0x20000
	ds_read_b128 v[30:33], v4
	ds_read_b128 v[34:37], v4 offset:64
	ds_read_b128 v[38:41], v4 offset:128
	ds_read_b128 v[42:45], v4 offset:192
	ds_read_b128 v[46:49], v4 offset:256
	ds_read_b128 v[50:53], v4 offset:320
	ds_read_b128 v[54:57], v4 offset:384
	ds_read_b128 v[58:61], v4 offset:448
	ds_read_b128 v[62:65], v4 offset:512
	ds_read_b128 v[66:69], v4 offset:576
	ds_read_b128 v[70:73], v4 offset:640
	ds_read_b128 v[74:77], v4 offset:704
	ds_read_b128 v[78:81], v4 offset:768
	ds_read_b128 v[82:85], v4 offset:832
	ds_read_b128 v[86:89], v4 offset:896
	ds_read_b128 v[90:93], v4 offset:960
	v_add_u32_e32 v4, 0x400, v4
	s_waitcnt vmcnt(59) lgkmcnt(15)
	v_pk_fma_f32 v[10:11], v[32:33], v[94:95], v[10:11] op_sel_hi:[1,0,1]
	v_pk_fma_f32 v[12:13], v[30:31], v[94:95], v[12:13] op_sel_hi:[1,0,1]
	s_waitcnt vmcnt(58) lgkmcnt(14)
	v_pk_fma_f32 v[10:11], v[36:37], v[94:95], v[10:11] op_sel:[0,1,0]
	v_pk_fma_f32 v[12:13], v[34:35], v[94:95], v[12:13] op_sel:[0,1,0]
	s_waitcnt vmcnt(57) lgkmcnt(13)
	v_pk_fma_f32 v[10:11], v[40:41], v[96:97], v[10:11] op_sel_hi:[1,0,1]
	v_pk_fma_f32 v[12:13], v[38:39], v[96:97], v[12:13] op_sel_hi:[1,0,1]
	s_waitcnt vmcnt(56) lgkmcnt(12)
	v_pk_fma_f32 v[10:11], v[44:45], v[96:97], v[10:11] op_sel:[0,1,0]
	v_pk_fma_f32 v[12:13], v[42:43], v[96:97], v[12:13] op_sel:[0,1,0]
	global_load_dword v154, v[158:159], off offset:2048
	global_load_dword v155, v[158:159], off offset:2560
	global_load_dword v156, v[158:159], off offset:3072
	global_load_dword v157, v[158:159], off offset:3584
	s_waitcnt vmcnt(59) lgkmcnt(11)
	v_pk_fma_f32 v[10:11], v[48:49], v[98:99], v[10:11] op_sel_hi:[1,0,1]
	v_pk_fma_f32 v[12:13], v[46:47], v[98:99], v[12:13] op_sel_hi:[1,0,1]
	s_waitcnt vmcnt(58) lgkmcnt(10)
	v_pk_fma_f32 v[10:11], v[52:53], v[98:99], v[10:11] op_sel:[0,1,0]
	v_pk_fma_f32 v[12:13], v[50:51], v[98:99], v[12:13] op_sel:[0,1,0]
	s_waitcnt vmcnt(57) lgkmcnt(9)
	v_pk_fma_f32 v[10:11], v[56:57], v[100:101], v[10:11] op_sel_hi:[1,0,1]
	v_pk_fma_f32 v[12:13], v[54:55], v[100:101], v[12:13] op_sel_hi:[1,0,1]
	s_waitcnt vmcnt(56) lgkmcnt(8)
	v_pk_fma_f32 v[10:11], v[60:61], v[100:101], v[10:11] op_sel:[0,1,0]
	v_pk_fma_f32 v[12:13], v[58:59], v[100:101], v[12:13] op_sel:[0,1,0]
	s_waitcnt vmcnt(55) lgkmcnt(7)
	v_pk_fma_f32 v[10:11], v[64:65], v[102:103], v[10:11] op_sel_hi:[1,0,1]
	v_pk_fma_f32 v[12:13], v[62:63], v[102:103], v[12:13] op_sel_hi:[1,0,1]
	s_waitcnt vmcnt(54) lgkmcnt(6)
	v_pk_fma_f32 v[10:11], v[68:69], v[102:103], v[10:11] op_sel:[0,1,0]
	v_pk_fma_f32 v[12:13], v[66:67], v[102:103], v[12:13] op_sel:[0,1,0]
	s_waitcnt vmcnt(53) lgkmcnt(5)
	v_pk_fma_f32 v[10:11], v[72:73], v[104:105], v[10:11] op_sel_hi:[1,0,1]
	v_pk_fma_f32 v[12:13], v[70:71], v[104:105], v[12:13] op_sel_hi:[1,0,1]
	s_waitcnt vmcnt(52) lgkmcnt(4)
	v_pk_fma_f32 v[10:11], v[76:77], v[104:105], v[10:11] op_sel:[0,1,0]
	v_pk_fma_f32 v[12:13], v[74:75], v[104:105], v[12:13] op_sel:[0,1,0]
	s_waitcnt vmcnt(51) lgkmcnt(3)
	v_pk_fma_f32 v[10:11], v[80:81], v[106:107], v[10:11] op_sel_hi:[1,0,1]
	v_pk_fma_f32 v[12:13], v[78:79], v[106:107], v[12:13] op_sel_hi:[1,0,1]
	s_waitcnt vmcnt(50) lgkmcnt(2)
	v_pk_fma_f32 v[10:11], v[84:85], v[106:107], v[10:11] op_sel:[0,1,0]
	v_pk_fma_f32 v[12:13], v[82:83], v[106:107], v[12:13] op_sel:[0,1,0]
	s_waitcnt vmcnt(49) lgkmcnt(1)
	v_pk_fma_f32 v[10:11], v[88:89], v[108:109], v[10:11] op_sel_hi:[1,0,1]
	v_pk_fma_f32 v[12:13], v[86:87], v[108:109], v[12:13] op_sel_hi:[1,0,1]
	s_waitcnt vmcnt(48) lgkmcnt(0)
	v_pk_fma_f32 v[10:11], v[92:93], v[108:109], v[10:11] op_sel:[0,1,0]
	v_pk_fma_f32 v[12:13], v[90:91], v[108:109], v[12:13] op_sel:[0,1,0]
	ds_read_b128 v[30:33], v4
	ds_read_b128 v[34:37], v4 offset:64
	ds_read_b128 v[38:41], v4 offset:128
	ds_read_b128 v[42:45], v4 offset:192
	ds_read_b128 v[46:49], v4 offset:256
	ds_read_b128 v[50:53], v4 offset:320
	ds_read_b128 v[54:57], v4 offset:384
	ds_read_b128 v[58:61], v4 offset:448
	ds_read_b128 v[62:65], v4 offset:512
	ds_read_b128 v[66:69], v4 offset:576
	ds_read_b128 v[70:73], v4 offset:640
	ds_read_b128 v[74:77], v4 offset:704
	ds_read_b128 v[78:81], v4 offset:768
	ds_read_b128 v[82:85], v4 offset:832
	ds_read_b128 v[86:89], v4 offset:896
	ds_read_b128 v[90:93], v4 offset:960
	v_add_u32_e32 v4, 0x400, v4
	s_waitcnt vmcnt(47) lgkmcnt(15)
	v_pk_fma_f32 v[10:11], v[32:33], v[110:111], v[10:11] op_sel_hi:[1,0,1]
	v_pk_fma_f32 v[12:13], v[30:31], v[110:111], v[12:13] op_sel_hi:[1,0,1]
	s_waitcnt vmcnt(46) lgkmcnt(14)
	v_pk_fma_f32 v[10:11], v[36:37], v[110:111], v[10:11] op_sel:[0,1,0]
	v_pk_fma_f32 v[12:13], v[34:35], v[110:111], v[12:13] op_sel:[0,1,0]
	s_waitcnt vmcnt(45) lgkmcnt(13)
	v_pk_fma_f32 v[10:11], v[40:41], v[112:113], v[10:11] op_sel_hi:[1,0,1]
	v_pk_fma_f32 v[12:13], v[38:39], v[112:113], v[12:13] op_sel_hi:[1,0,1]
	s_waitcnt vmcnt(44) lgkmcnt(12)
	v_pk_fma_f32 v[10:11], v[44:45], v[112:113], v[10:11] op_sel:[0,1,0]
	v_pk_fma_f32 v[12:13], v[42:43], v[112:113], v[12:13] op_sel:[0,1,0]
	s_waitcnt vmcnt(43) lgkmcnt(11)
	v_pk_fma_f32 v[10:11], v[48:49], v[114:115], v[10:11] op_sel_hi:[1,0,1]
	v_pk_fma_f32 v[12:13], v[46:47], v[114:115], v[12:13] op_sel_hi:[1,0,1]
	s_waitcnt vmcnt(42) lgkmcnt(10)
	v_pk_fma_f32 v[10:11], v[52:53], v[114:115], v[10:11] op_sel:[0,1,0]
	v_pk_fma_f32 v[12:13], v[50:51], v[114:115], v[12:13] op_sel:[0,1,0]
	s_waitcnt vmcnt(41) lgkmcnt(9)
	v_pk_fma_f32 v[10:11], v[56:57], v[116:117], v[10:11] op_sel_hi:[1,0,1]
	v_pk_fma_f32 v[12:13], v[54:55], v[116:117], v[12:13] op_sel_hi:[1,0,1]
	s_waitcnt vmcnt(40) lgkmcnt(8)
	v_pk_fma_f32 v[10:11], v[60:61], v[116:117], v[10:11] op_sel:[0,1,0]
	v_pk_fma_f32 v[12:13], v[58:59], v[116:117], v[12:13] op_sel:[0,1,0]
	s_waitcnt vmcnt(39) lgkmcnt(7)
	v_pk_fma_f32 v[10:11], v[64:65], v[118:119], v[10:11] op_sel_hi:[1,0,1]
	v_pk_fma_f32 v[12:13], v[62:63], v[118:119], v[12:13] op_sel_hi:[1,0,1]
	s_waitcnt vmcnt(38) lgkmcnt(6)
	v_pk_fma_f32 v[10:11], v[68:69], v[118:119], v[10:11] op_sel:[0,1,0]
	v_pk_fma_f32 v[12:13], v[66:67], v[118:119], v[12:13] op_sel:[0,1,0]
	s_waitcnt vmcnt(37) lgkmcnt(5)
	v_pk_fma_f32 v[10:11], v[72:73], v[120:121], v[10:11] op_sel_hi:[1,0,1]
	v_pk_fma_f32 v[12:13], v[70:71], v[120:121], v[12:13] op_sel_hi:[1,0,1]
	s_waitcnt vmcnt(36) lgkmcnt(4)
	v_pk_fma_f32 v[10:11], v[76:77], v[120:121], v[10:11] op_sel:[0,1,0]
	v_pk_fma_f32 v[12:13], v[74:75], v[120:121], v[12:13] op_sel:[0,1,0]
	s_waitcnt vmcnt(35) lgkmcnt(3)
	v_pk_fma_f32 v[10:11], v[80:81], v[122:123], v[10:11] op_sel_hi:[1,0,1]
	v_pk_fma_f32 v[12:13], v[78:79], v[122:123], v[12:13] op_sel_hi:[1,0,1]
	s_waitcnt vmcnt(34) lgkmcnt(2)
	v_pk_fma_f32 v[10:11], v[84:85], v[122:123], v[10:11] op_sel:[0,1,0]
	v_pk_fma_f32 v[12:13], v[82:83], v[122:123], v[12:13] op_sel:[0,1,0]
	s_waitcnt vmcnt(33) lgkmcnt(1)
	v_pk_fma_f32 v[10:11], v[88:89], v[124:125], v[10:11] op_sel_hi:[1,0,1]
	v_pk_fma_f32 v[12:13], v[86:87], v[124:125], v[12:13] op_sel_hi:[1,0,1]
	s_waitcnt vmcnt(32) lgkmcnt(0)
	v_pk_fma_f32 v[10:11], v[92:93], v[124:125], v[10:11] op_sel:[0,1,0]
	v_pk_fma_f32 v[12:13], v[90:91], v[124:125], v[12:13] op_sel:[0,1,0]
	ds_read_b128 v[30:33], v4
	ds_read_b128 v[34:37], v4 offset:64
	ds_read_b128 v[38:41], v4 offset:128
	ds_read_b128 v[42:45], v4 offset:192
	ds_read_b128 v[46:49], v4 offset:256
	ds_read_b128 v[50:53], v4 offset:320
	ds_read_b128 v[54:57], v4 offset:384
	ds_read_b128 v[58:61], v4 offset:448
	ds_read_b128 v[62:65], v4 offset:512
	ds_read_b128 v[66:69], v4 offset:576
	ds_read_b128 v[70:73], v4 offset:640
	ds_read_b128 v[74:77], v4 offset:704
	ds_read_b128 v[78:81], v4 offset:768
	ds_read_b128 v[82:85], v4 offset:832
	ds_read_b128 v[86:89], v4 offset:896
	ds_read_b128 v[90:93], v4 offset:960
	v_add_u32_e32 v4, 0x400, v4
	s_waitcnt vmcnt(31) lgkmcnt(15)
	v_pk_fma_f32 v[10:11], v[32:33], v[126:127], v[10:11] op_sel_hi:[1,0,1]
	v_pk_fma_f32 v[12:13], v[30:31], v[126:127], v[12:13] op_sel_hi:[1,0,1]
	s_waitcnt vmcnt(30) lgkmcnt(14)
	v_pk_fma_f32 v[10:11], v[36:37], v[126:127], v[10:11] op_sel:[0,1,0]
	v_pk_fma_f32 v[12:13], v[34:35], v[126:127], v[12:13] op_sel:[0,1,0]
	s_waitcnt vmcnt(29) lgkmcnt(13)
	v_pk_fma_f32 v[10:11], v[40:41], v[128:129], v[10:11] op_sel_hi:[1,0,1]
	v_pk_fma_f32 v[12:13], v[38:39], v[128:129], v[12:13] op_sel_hi:[1,0,1]
	s_waitcnt vmcnt(28) lgkmcnt(12)
	v_pk_fma_f32 v[10:11], v[44:45], v[128:129], v[10:11] op_sel:[0,1,0]
	v_pk_fma_f32 v[12:13], v[42:43], v[128:129], v[12:13] op_sel:[0,1,0]
	s_waitcnt vmcnt(27) lgkmcnt(11)
	v_pk_fma_f32 v[10:11], v[48:49], v[130:131], v[10:11] op_sel_hi:[1,0,1]
	v_pk_fma_f32 v[12:13], v[46:47], v[130:131], v[12:13] op_sel_hi:[1,0,1]
	s_waitcnt vmcnt(26) lgkmcnt(10)
	v_pk_fma_f32 v[10:11], v[52:53], v[130:131], v[10:11] op_sel:[0,1,0]
	v_pk_fma_f32 v[12:13], v[50:51], v[130:131], v[12:13] op_sel:[0,1,0]
	s_waitcnt vmcnt(25) lgkmcnt(9)
	v_pk_fma_f32 v[10:11], v[56:57], v[132:133], v[10:11] op_sel_hi:[1,0,1]
	v_pk_fma_f32 v[12:13], v[54:55], v[132:133], v[12:13] op_sel_hi:[1,0,1]
	s_waitcnt vmcnt(24) lgkmcnt(8)
	v_pk_fma_f32 v[10:11], v[60:61], v[132:133], v[10:11] op_sel:[0,1,0]
	v_pk_fma_f32 v[12:13], v[58:59], v[132:133], v[12:13] op_sel:[0,1,0]
	s_waitcnt vmcnt(23) lgkmcnt(7)
	v_pk_fma_f32 v[10:11], v[64:65], v[134:135], v[10:11] op_sel_hi:[1,0,1]
	v_pk_fma_f32 v[12:13], v[62:63], v[134:135], v[12:13] op_sel_hi:[1,0,1]
	s_waitcnt vmcnt(22) lgkmcnt(6)
	v_pk_fma_f32 v[10:11], v[68:69], v[134:135], v[10:11] op_sel:[0,1,0]
	v_pk_fma_f32 v[12:13], v[66:67], v[134:135], v[12:13] op_sel:[0,1,0]
	s_waitcnt vmcnt(21) lgkmcnt(5)
	v_pk_fma_f32 v[10:11], v[72:73], v[136:137], v[10:11] op_sel_hi:[1,0,1]
	v_pk_fma_f32 v[12:13], v[70:71], v[136:137], v[12:13] op_sel_hi:[1,0,1]
	s_waitcnt vmcnt(20) lgkmcnt(4)
	v_pk_fma_f32 v[10:11], v[76:77], v[136:137], v[10:11] op_sel:[0,1,0]
	v_pk_fma_f32 v[12:13], v[74:75], v[136:137], v[12:13] op_sel:[0,1,0]
	s_waitcnt vmcnt(19) lgkmcnt(3)
	v_pk_fma_f32 v[10:11], v[80:81], v[138:139], v[10:11] op_sel_hi:[1,0,1]
	v_pk_fma_f32 v[12:13], v[78:79], v[138:139], v[12:13] op_sel_hi:[1,0,1]
	s_waitcnt vmcnt(18) lgkmcnt(2)
	v_pk_fma_f32 v[10:11], v[84:85], v[138:139], v[10:11] op_sel:[0,1,0]
	v_pk_fma_f32 v[12:13], v[82:83], v[138:139], v[12:13] op_sel:[0,1,0]
	s_waitcnt vmcnt(17) lgkmcnt(1)
	v_pk_fma_f32 v[10:11], v[88:89], v[140:141], v[10:11] op_sel_hi:[1,0,1]
	v_pk_fma_f32 v[12:13], v[86:87], v[140:141], v[12:13] op_sel_hi:[1,0,1]
	s_waitcnt vmcnt(16) lgkmcnt(0)
	v_pk_fma_f32 v[10:11], v[92:93], v[140:141], v[10:11] op_sel:[0,1,0]
	v_pk_fma_f32 v[12:13], v[90:91], v[140:141], v[12:13] op_sel:[0,1,0]
	ds_read_b128 v[30:33], v4
	ds_read_b128 v[34:37], v4 offset:64
	ds_read_b128 v[38:41], v4 offset:128
	ds_read_b128 v[42:45], v4 offset:192
	ds_read_b128 v[46:49], v4 offset:256
	ds_read_b128 v[50:53], v4 offset:320
	ds_read_b128 v[54:57], v4 offset:384
	ds_read_b128 v[58:61], v4 offset:448
	ds_read_b128 v[62:65], v4 offset:512
	ds_read_b128 v[66:69], v4 offset:576
	ds_read_b128 v[70:73], v4 offset:640
	ds_read_b128 v[74:77], v4 offset:704
	ds_read_b128 v[78:81], v4 offset:768
	ds_read_b128 v[82:85], v4 offset:832
	ds_read_b128 v[86:89], v4 offset:896
	ds_read_b128 v[90:93], v4 offset:960
	v_add_u32_e32 v4, 0x400, v4
	s_waitcnt vmcnt(15) lgkmcnt(15)
	v_pk_fma_f32 v[10:11], v[32:33], v[142:143], v[10:11] op_sel_hi:[1,0,1]
	v_pk_fma_f32 v[12:13], v[30:31], v[142:143], v[12:13] op_sel_hi:[1,0,1]
	s_waitcnt vmcnt(14) lgkmcnt(14)
	v_pk_fma_f32 v[10:11], v[36:37], v[142:143], v[10:11] op_sel:[0,1,0]
	v_pk_fma_f32 v[12:13], v[34:35], v[142:143], v[12:13] op_sel:[0,1,0]
	s_waitcnt vmcnt(13) lgkmcnt(13)
	v_pk_fma_f32 v[10:11], v[40:41], v[144:145], v[10:11] op_sel_hi:[1,0,1]
	v_pk_fma_f32 v[12:13], v[38:39], v[144:145], v[12:13] op_sel_hi:[1,0,1]
	s_waitcnt vmcnt(12) lgkmcnt(12)
	v_pk_fma_f32 v[10:11], v[44:45], v[144:145], v[10:11] op_sel:[0,1,0]
	v_pk_fma_f32 v[12:13], v[42:43], v[144:145], v[12:13] op_sel:[0,1,0]
	s_waitcnt vmcnt(11) lgkmcnt(11)
	v_pk_fma_f32 v[10:11], v[48:49], v[146:147], v[10:11] op_sel_hi:[1,0,1]
	v_pk_fma_f32 v[12:13], v[46:47], v[146:147], v[12:13] op_sel_hi:[1,0,1]
	s_waitcnt vmcnt(10) lgkmcnt(10)
	v_pk_fma_f32 v[10:11], v[52:53], v[146:147], v[10:11] op_sel:[0,1,0]
	v_pk_fma_f32 v[12:13], v[50:51], v[146:147], v[12:13] op_sel:[0,1,0]
	s_waitcnt vmcnt(9) lgkmcnt(9)
	v_pk_fma_f32 v[10:11], v[56:57], v[148:149], v[10:11] op_sel_hi:[1,0,1]
	v_pk_fma_f32 v[12:13], v[54:55], v[148:149], v[12:13] op_sel_hi:[1,0,1]
	s_waitcnt vmcnt(8) lgkmcnt(8)
	v_pk_fma_f32 v[10:11], v[60:61], v[148:149], v[10:11] op_sel:[0,1,0]
	v_pk_fma_f32 v[12:13], v[58:59], v[148:149], v[12:13] op_sel:[0,1,0]
	s_waitcnt vmcnt(7) lgkmcnt(7)
	v_pk_fma_f32 v[10:11], v[64:65], v[150:151], v[10:11] op_sel_hi:[1,0,1]
	v_pk_fma_f32 v[12:13], v[62:63], v[150:151], v[12:13] op_sel_hi:[1,0,1]
	s_waitcnt vmcnt(6) lgkmcnt(6)
	v_pk_fma_f32 v[10:11], v[68:69], v[150:151], v[10:11] op_sel:[0,1,0]
	v_pk_fma_f32 v[12:13], v[66:67], v[150:151], v[12:13] op_sel:[0,1,0]
	s_waitcnt vmcnt(5) lgkmcnt(5)
	v_pk_fma_f32 v[10:11], v[72:73], v[152:153], v[10:11] op_sel_hi:[1,0,1]
	v_pk_fma_f32 v[12:13], v[70:71], v[152:153], v[12:13] op_sel_hi:[1,0,1]
	s_waitcnt vmcnt(4) lgkmcnt(4)
	v_pk_fma_f32 v[10:11], v[76:77], v[152:153], v[10:11] op_sel:[0,1,0]
	v_pk_fma_f32 v[12:13], v[74:75], v[152:153], v[12:13] op_sel:[0,1,0]
	s_waitcnt vmcnt(3) lgkmcnt(3)
	v_pk_fma_f32 v[10:11], v[80:81], v[154:155], v[10:11] op_sel_hi:[1,0,1]
	v_pk_fma_f32 v[12:13], v[78:79], v[154:155], v[12:13] op_sel_hi:[1,0,1]
	s_waitcnt vmcnt(2) lgkmcnt(2)
	v_pk_fma_f32 v[10:11], v[84:85], v[154:155], v[10:11] op_sel:[0,1,0]
	v_pk_fma_f32 v[12:13], v[82:83], v[154:155], v[12:13] op_sel:[0,1,0]
	s_waitcnt vmcnt(1) lgkmcnt(1)
	v_pk_fma_f32 v[10:11], v[88:89], v[156:157], v[10:11] op_sel_hi:[1,0,1]
	v_pk_fma_f32 v[12:13], v[86:87], v[156:157], v[12:13] op_sel_hi:[1,0,1]
	s_waitcnt vmcnt(0) lgkmcnt(0)
	v_pk_fma_f32 v[10:11], v[92:93], v[156:157], v[10:11] op_sel:[0,1,0]
	v_pk_fma_f32 v[12:13], v[90:91], v[156:157], v[12:13] op_sel:[0,1,0]
	s_cbranch_scc0 .LBB0_584
	s_and_b64 s[14:15], s[14:15], exec
	s_cselect_b32 s10, s22, 0x1cdb3400
	s_add_u32 s14, s76, s10
	v_add_u32_e32 v30, s27, v14
	s_addc_u32 s15, s77, 0
	v_add_lshl_u32 v4, v30, s28, 8
	v_lshl_add_u64 v[8:9], s[14:15], 0, v[4:5]
	v_lshlrev_b32_e32 v4, 1, v2
	v_lshl_add_u64 v[8:9], v[8:9], 0, v[4:5]
	v_cvt_pk_bf16_f32 v4, v12, s0
	v_cmp_gt_u32_e32 vcc, s0, v30
	s_add_i32 s26, s26, s79
	s_cmpk_gt_i32 s26, 0xff
	v_cndmask_b32_e32 v4, 0, v4, vcc
	global_store_short v[8:9], v4, off
	v_cvt_pk_bf16_f32 v4, v13, s0
	v_cmp_gt_u32_e32 vcc, s23, v30
	s_nop 1
	v_cndmask_b32_e32 v4, 0, v4, vcc
	global_store_short v[8:9], v4, off offset:256
	v_cvt_pk_bf16_f32 v4, v10, s0
	v_cmp_gt_u32_e32 vcc, s24, v30
	s_nop 1
	v_cndmask_b32_e32 v4, 0, v4, vcc
	global_store_short v[8:9], v4, off offset:512
	v_cvt_pk_bf16_f32 v4, v11, s0
	v_cmp_gt_u32_e32 vcc, s25, v30
	s_nop 1
	v_cndmask_b32_e32 v4, 0, v4, vcc
	global_store_short v[8:9], v4, off offset:768
	s_barrier
	s_cbranch_scc0 .LBB0_573

.LBB0_673:
	s_and_b32 s98, s77, 1
	s_mul_i32 s98, s98, 0x4400
	v_add_u32_e32 v171, s98, v194
	ds_read_b128 v[172:175], v171
	ds_read_b128 v[184:187], v171 offset:32
	ds_read_b128 v[196:199], v171 offset:8704
	ds_read_b128 v[200:203], v171 offset:8736
	s_cmp_lt_u32 s77, s79
	s_cselect_b64 s[80:81], -1, 0
	s_cmp_ge_u32 s77, s79
	s_cbranch_scc1 .LBB0_675
	v_lshl_add_u64 v[66:67], v[162:163], 0, s[86:87]
	v_add_co_u32_e32 v68, vcc, 0xb92b000, v66
	s_nop 1
	v_addc_co_u32_e32 v69, vcc, 0, v67, vcc
	v_add_co_u32_e32 v66, vcc, 0xb92d000, v66
	s_nop 1
	v_addc_co_u32_e32 v67, vcc, 0, v67, vcc
	global_load_dwordx4 v[98:101], v[68:69], off offset:1024
	global_load_dwordx4 v[102:105], v[66:67], off offset:1024
.LBB0_675:
	s_add_i32 s85, s86, s89
	s_and_b32 s84, s77, 1
	s_addk_i32 s85, 0xc000
	s_add_u32 vcc_lo, s96, s85
	s_addc_u32 vcc_hi, s78, 0
	v_lshl_add_u64 v[66:67], vcc, 0, v[178:179]
	v_add_co_u32_e32 v68, vcc, s92, v66
	s_mul_i32 s85, s84, 0x4400
	s_nop 0
	v_addc_co_u32_e32 v69, vcc, 0, v67, vcc
	global_load_dwordx4 v[146:149], v[66:67], off
	global_load_dwordx4 v[150:153], v[68:69], off
	v_lshrrev_b32_e32 v66, s1, v169
	v_and_b32_e32 v66, 1, v66
	v_cmp_eq_u32_e32 vcc, 1, v66
	s_nop 1
	v_cndmask_b32_e64 v66, v188, -v170, vcc
	v_mov_b32_e32 v67, v66
	v_mov_b32_e32 v68, v66
	v_mov_b32_e32 v69, v66
	v_mov_b32_e32 v70, v66
	v_mov_b32_e32 v71, v66
	v_mov_b32_e32 v72, v66
	v_mov_b32_e32 v73, v66
	v_mov_b32_e32 v74, v66
	v_mov_b32_e32 v75, v66
	v_mov_b32_e32 v76, v66
	v_mov_b32_e32 v77, v66
	v_mov_b32_e32 v78, v66
	v_mov_b32_e32 v79, v66
	v_mov_b32_e32 v80, v66
	v_mov_b32_e32 v81, v66
	s_waitcnt lgkmcnt(3)
	s_nop 0
	v_mfma_f32_32x32x16_bf16 v[82:97], v[172:175], v[114:117], v[66:81]
	ds_read_b128 v[172:175], v171 offset:64
	ds_read_b128 v[204:207], v171 offset:96
	ds_read_b128 v[208:211], v171 offset:8768
	ds_read_b128 v[212:215], v171 offset:8800
	s_waitcnt lgkmcnt(6)
	v_mfma_f32_32x32x16_bf16 v[82:97], v[184:187], v[118:121], v[82:97]
	s_waitcnt lgkmcnt(3)
	v_mfma_f32_32x32x16_bf16 v[82:97], v[172:175], v[122:125], v[82:97]
	ds_read_b128 v[172:175], v171 offset:128
	ds_read_b128 v[184:187], v171 offset:160
	ds_read_b128 v[216:219], v171 offset:8832
	ds_read_b128 v[220:223], v171 offset:8864
	s_waitcnt lgkmcnt(6)
	v_mfma_f32_32x32x16_bf16 v[82:97], v[204:207], v[126:129], v[82:97]
	s_waitcnt lgkmcnt(3)
	v_mfma_f32_32x32x16_bf16 v[82:97], v[172:175], v[130:133], v[82:97]
	ds_read_b128 v[172:175], v171 offset:192
	ds_read_b128 v[204:207], v171 offset:224
	ds_read_b128 v[224:227], v171 offset:8896
	ds_read_b128 v[228:231], v171 offset:8928
	s_waitcnt lgkmcnt(6)
	v_mfma_f32_32x32x16_bf16 v[82:97], v[184:187], v[134:137], v[82:97]
	s_waitcnt lgkmcnt(3)
	v_mfma_f32_32x32x16_bf16 v[82:97], v[172:175], v[138:141], v[82:97]
	s_waitcnt lgkmcnt(2)
	v_mfma_f32_32x32x16_bf16 v[82:97], v[204:207], v[142:145], v[82:97]
	v_mfma_f32_32x32x16_bf16 v[66:81], v[196:199], v[114:117], v[66:81]
	s_xor_b32 s85, s84, 1
	s_mul_i32 vcc_lo, s85, 0x5000
	v_add_u32_e32 v171, vcc_lo, v195
	ds_read_b64_tr_b16 v[174:175], v171 offset:37376
	s_nop 6
	v_exp_f32_e32 v82, v82
	v_exp_f32_e32 v83, v83
	v_exp_f32_e32 v84, v84
	v_mfma_f32_32x32x16_bf16 v[66:81], v[200:203], v[118:121], v[66:81]
	ds_read_b64_tr_b16 v[172:173], v171 offset:34816
	ds_read_b64_tr_b16 v[184:185], v171 offset:34880
	ds_read_b64_tr_b16 v[196:197], v171 offset:34944
	ds_read_b64_tr_b16 v[200:201], v171 offset:35008
	ds_read_b64_tr_b16 v[186:187], v171 offset:37440
	ds_read_b64_tr_b16 v[198:199], v171 offset:37504
	ds_read_b64_tr_b16 v[202:203], v171 offset:37568
	v_exp_f32_e32 v85, v85
	v_mfma_f32_32x32x16_bf16 v[66:81], v[208:211], v[122:125], v[66:81]
	v_mfma_f32_32x32x16_bf16 v[66:81], v[212:215], v[126:129], v[66:81]
	v_mfma_f32_32x32x16_bf16 v[66:81], v[216:219], v[130:133], v[66:81]
	v_mfma_f32_32x32x16_bf16 v[66:81], v[220:223], v[134:137], v[66:81]
	s_waitcnt lgkmcnt(9)
	v_mfma_f32_32x32x16_bf16 v[66:81], v[224:227], v[138:141], v[66:81]
	s_waitcnt lgkmcnt(8)
	v_mfma_f32_32x32x16_bf16 v[66:81], v[228:231], v[142:145], v[66:81]
	s_waitcnt lgkmcnt(6)
	v_mfma_f32_32x32x16_bf16 v[50:65], v[172:175], v[158:161], v[50:65]
	s_nop 9
	v_exp_f32_e32 v66, v66
	v_exp_f32_e32 v67, v67
	v_exp_f32_e32 v68, v68
	v_exp_f32_e32 v69, v69
	v_add_f32_e32 v172, v179, v82
	v_add_f32_e32 v173, v179, v66
	s_waitcnt lgkmcnt(2)
	v_mfma_f32_32x32x16_bf16 v[34:49], v[184:187], v[158:161], v[34:49]
	v_add_f32_e32 v172, v172, v83
	v_add_f32_e32 v173, v173, v67
	s_nop 0
	v_add_f32_e32 v172, v172, v84
	v_add_f32_e32 v173, v173, v68
	s_nop 0
	v_add_f32_e32 v176, v172, v85
	s_waitcnt lgkmcnt(1)
	v_mfma_f32_32x32x16_bf16 v[18:33], v[196:199], v[158:161], v[18:33]
	v_add_f32_e32 v177, v173, v69
	s_waitcnt lgkmcnt(0)
	v_mfma_f32_32x32x16_bf16 v[2:17], v[200:203], v[158:161], v[2:17]
	ds_read_b64_tr_b16 v[160:161], v171 offset:42496
	ds_read_b64_tr_b16 v[158:159], v171 offset:39936
	ds_read_b64_tr_b16 v[172:173], v171 offset:40000
	v_exp_f32_e32 v86, v86
	v_exp_f32_e32 v70, v70
	v_exp_f32_e32 v87, v87
	s_waitcnt lgkmcnt(1)
	v_mfma_f32_32x32x16_bf16 v[50:65], v[158:161], v[154:157], v[50:65]
	ds_read_b64_tr_b16 v[174:175], v171 offset:42560
	ds_read_b64_tr_b16 v[158:159], v171 offset:40064
	ds_read_b64_tr_b16 v[184:185], v171 offset:40128
	ds_read_b64_tr_b16 v[160:161], v171 offset:42624
	ds_read_b64_tr_b16 v[186:187], v171 offset:42688
	v_exp_f32_e32 v71, v71
	v_exp_f32_e32 v88, v88
	v_exp_f32_e32 v72, v72
	v_exp_f32_e32 v89, v89
	v_exp_f32_e32 v73, v73
	s_waitcnt lgkmcnt(4)
	v_mfma_f32_32x32x16_bf16 v[34:49], v[172:175], v[154:157], v[34:49]
	v_add_f32_e32 v172, v176, v86
	v_add_f32_e32 v173, v177, v70
	s_nop 0
	v_add_f32_e32 v172, v172, v87
	v_add_f32_e32 v173, v173, v71
	s_waitcnt lgkmcnt(1)
	v_mfma_f32_32x32x16_bf16 v[18:33], v[158:161], v[154:157], v[18:33]
	v_add_f32_e32 v158, v172, v88
	v_add_f32_e32 v159, v173, v72
	s_nop 0
	v_add_f32_e32 v176, v158, v89
	v_add_f32_e32 v177, v159, v73
	s_waitcnt lgkmcnt(0)
	v_mfma_f32_32x32x16_bf16 v[2:17], v[184:187], v[154:157], v[2:17]
	ds_read_b64_tr_b16 v[156:157], v171 offset:47616
	ds_read_b64_tr_b16 v[154:155], v171 offset:45056
	ds_read_b64_tr_b16 v[158:159], v171 offset:45120
	v_exp_f32_e32 v90, v90
	v_exp_f32_e32 v74, v74
	v_exp_f32_e32 v91, v91
	s_waitcnt lgkmcnt(1)
	v_mfma_f32_32x32x16_bf16 v[50:65], v[154:157], v[110:113], v[50:65]
	ds_read_b64_tr_b16 v[160:161], v171 offset:47680
	ds_read_b64_tr_b16 v[154:155], v171 offset:45184
	ds_read_b64_tr_b16 v[172:173], v171 offset:45248
	ds_read_b64_tr_b16 v[156:157], v171 offset:47744
	ds_read_b64_tr_b16 v[174:175], v171 offset:47808
	v_exp_f32_e32 v75, v75
	v_exp_f32_e32 v92, v92
	v_exp_f32_e32 v76, v76
	v_exp_f32_e32 v93, v93
	v_exp_f32_e32 v77, v77
	s_waitcnt lgkmcnt(4)
	v_mfma_f32_32x32x16_bf16 v[34:49], v[158:161], v[110:113], v[34:49]
	v_add_f32_e32 v158, v176, v90
	v_add_f32_e32 v159, v177, v74
	s_nop 0
	v_add_f32_e32 v158, v158, v91
	v_add_f32_e32 v159, v159, v75
	s_waitcnt lgkmcnt(1)
	v_mfma_f32_32x32x16_bf16 v[18:33], v[154:157], v[110:113], v[18:33]
	v_add_f32_e32 v154, v158, v92
	v_add_f32_e32 v155, v159, v76
	s_nop 0
	v_add_f32_e32 v176, v154, v93
	v_add_f32_e32 v177, v155, v77
	s_waitcnt lgkmcnt(0)
	v_mfma_f32_32x32x16_bf16 v[2:17], v[172:175], v[110:113], v[2:17]
	ds_read_b64_tr_b16 v[112:113], v171 offset:52736
	ds_read_b64_tr_b16 v[110:111], v171 offset:50176
	ds_read_b64_tr_b16 v[154:155], v171 offset:50240
	v_exp_f32_e32 v94, v94
	v_exp_f32_e32 v78, v78
	v_exp_f32_e32 v95, v95
	s_waitcnt lgkmcnt(1)
	v_mfma_f32_32x32x16_bf16 v[50:65], v[110:113], v[106:109], v[50:65]
	ds_read_b64_tr_b16 v[156:157], v171 offset:52800
	ds_read_b64_tr_b16 v[110:111], v171 offset:50304
	ds_read_b64_tr_b16 v[158:159], v171 offset:50368
	ds_read_b64_tr_b16 v[112:113], v171 offset:52864
	ds_read_b64_tr_b16 v[160:161], v171 offset:52928
	v_exp_f32_e32 v79, v79
	v_exp_f32_e32 v96, v96
	v_exp_f32_e32 v80, v80
	v_exp_f32_e32 v97, v97
	v_exp_f32_e32 v81, v81
	s_waitcnt lgkmcnt(4)
	v_mfma_f32_32x32x16_bf16 v[34:49], v[154:157], v[106:109], v[34:49]
	v_add_f32_e32 v154, v176, v94
	v_add_f32_e32 v155, v177, v78
	s_nop 0
	v_add_f32_e32 v154, v154, v95
	v_add_f32_e32 v155, v155, v79
	s_waitcnt lgkmcnt(1)
	v_mfma_f32_32x32x16_bf16 v[18:33], v[110:113], v[106:109], v[18:33]
	v_add_f32_e32 v110, v154, v96
	v_add_f32_e32 v111, v155, v80
	s_nop 0
	v_add_f32_e32 v110, v110, v97
	v_add_f32_e32 v111, v111, v81
	s_waitcnt lgkmcnt(0)
	v_mfma_f32_32x32x16_bf16 v[2:17], v[158:161], v[106:109], v[2:17]
	v_add_f32_e32 v106, v110, v111
	v_cmp_lt_f32_e32 vcc, s94, v106
	s_cbranch_vccz .LBB0_677
	v_max_f32_e32 v107, v66, v66
	v_max_f32_e32 v108, v82, v82
	v_max_f32_e32 v107, v108, v107
	v_max3_f32 v107, v107, v83, v67
	v_max3_f32 v107, v107, v84, v68
	v_max3_f32 v107, v107, v85, v69
	v_max3_f32 v107, v107, v86, v70
	v_max3_f32 v107, v107, v87, v71
	v_max3_f32 v107, v107, v88, v72
	v_max3_f32 v107, v107, v89, v73
	v_max3_f32 v107, v107, v90, v74
	v_max3_f32 v107, v107, v91, v75
	v_max3_f32 v107, v107, v92, v76
	v_max3_f32 v107, v107, v93, v77
	v_max3_f32 v107, v107, v94, v78
	v_max3_f32 v107, v107, v95, v79
	v_max3_f32 v107, v107, v96, v80
	v_max3_f32 v107, v107, v97, v81
	v_mov_b32_e32 v108, v107
	v_mov_b32_e32 v109, v107
	s_nop 1
	v_permlane32_swap_b32_e32 v108, v109
	v_cndmask_b32_e64 v108, v108, v109, s[4:5]
	v_max_f32_e32 v108, v108, v108
	v_max_f32_e32 v107, v107, v108
	v_rcp_f32_e32 v108, v107
	v_log_f32_e32 v109, v107
	v_cmp_lt_f32_e32 vcc, s95, v107
	s_nop 1
	v_cndmask_b32_e32 v108, 1.0, v108, vcc
	v_cndmask_b32_e32 v107, 0, v109, vcc
	v_mul_f32_e32 v168, v168, v108
	v_add_f32_e32 v170, v170, v107
	v_pk_mul_f32 v[64:65], v[64:65], v[108:109] op_sel_hi:[1,0]
	v_pk_mul_f32 v[62:63], v[62:63], v[108:109] op_sel_hi:[1,0]
	v_pk_mul_f32 v[60:61], v[60:61], v[108:109] op_sel_hi:[1,0]
	v_pk_mul_f32 v[58:59], v[58:59], v[108:109] op_sel_hi:[1,0]
	v_pk_mul_f32 v[56:57], v[56:57], v[108:109] op_sel_hi:[1,0]
	v_pk_mul_f32 v[54:55], v[54:55], v[108:109] op_sel_hi:[1,0]
	v_pk_mul_f32 v[52:53], v[52:53], v[108:109] op_sel_hi:[1,0]
	v_pk_mul_f32 v[50:51], v[50:51], v[108:109] op_sel_hi:[1,0]
	v_pk_mul_f32 v[48:49], v[48:49], v[108:109] op_sel_hi:[1,0]
	v_pk_mul_f32 v[46:47], v[46:47], v[108:109] op_sel_hi:[1,0]
	v_pk_mul_f32 v[44:45], v[44:45], v[108:109] op_sel_hi:[1,0]
	v_pk_mul_f32 v[42:43], v[42:43], v[108:109] op_sel_hi:[1,0]
	v_pk_mul_f32 v[40:41], v[40:41], v[108:109] op_sel_hi:[1,0]
	v_pk_mul_f32 v[38:39], v[38:39], v[108:109] op_sel_hi:[1,0]
	v_pk_mul_f32 v[36:37], v[36:37], v[108:109] op_sel_hi:[1,0]
	v_pk_mul_f32 v[34:35], v[34:35], v[108:109] op_sel_hi:[1,0]
	v_pk_mul_f32 v[32:33], v[32:33], v[108:109] op_sel_hi:[1,0]
	v_pk_mul_f32 v[30:31], v[30:31], v[108:109] op_sel_hi:[1,0]
	v_pk_mul_f32 v[28:29], v[28:29], v[108:109] op_sel_hi:[1,0]
	v_pk_mul_f32 v[26:27], v[26:27], v[108:109] op_sel_hi:[1,0]
	v_pk_mul_f32 v[24:25], v[24:25], v[108:109] op_sel_hi:[1,0]
	v_pk_mul_f32 v[22:23], v[22:23], v[108:109] op_sel_hi:[1,0]
	v_pk_mul_f32 v[20:21], v[20:21], v[108:109] op_sel_hi:[1,0]
	v_pk_mul_f32 v[18:19], v[18:19], v[108:109] op_sel_hi:[1,0]
	v_pk_mul_f32 v[16:17], v[16:17], v[108:109] op_sel_hi:[1,0]
	v_pk_mul_f32 v[14:15], v[14:15], v[108:109] op_sel_hi:[1,0]
	v_pk_mul_f32 v[12:13], v[12:13], v[108:109] op_sel_hi:[1,0]
	v_pk_mul_f32 v[10:11], v[10:11], v[108:109] op_sel_hi:[1,0]
	v_pk_mul_f32 v[8:9], v[8:9], v[108:109] op_sel_hi:[1,0]
	v_pk_mul_f32 v[6:7], v[6:7], v[108:109] op_sel_hi:[1,0]
	v_pk_mul_f32 v[4:5], v[4:5], v[108:109] op_sel_hi:[1,0]
	v_pk_mul_f32 v[2:3], v[2:3], v[108:109] op_sel_hi:[1,0]
	v_pk_mul_f32 v[96:97], v[96:97], v[108:109] op_sel_hi:[1,0]
	v_pk_mul_f32 v[94:95], v[94:95], v[108:109] op_sel_hi:[1,0]
	v_pk_mul_f32 v[92:93], v[92:93], v[108:109] op_sel_hi:[1,0]
	v_pk_mul_f32 v[90:91], v[90:91], v[108:109] op_sel_hi:[1,0]
	v_pk_mul_f32 v[88:89], v[88:89], v[108:109] op_sel_hi:[1,0]
	v_pk_mul_f32 v[86:87], v[86:87], v[108:109] op_sel_hi:[1,0]
	v_pk_mul_f32 v[84:85], v[84:85], v[108:109] op_sel_hi:[1,0]
	v_pk_mul_f32 v[82:83], v[82:83], v[108:109] op_sel_hi:[1,0]
	v_pk_mul_f32 v[80:81], v[80:81], v[108:109] op_sel_hi:[1,0]
	v_pk_mul_f32 v[78:79], v[78:79], v[108:109] op_sel_hi:[1,0]
	v_pk_mul_f32 v[76:77], v[76:77], v[108:109] op_sel_hi:[1,0]
	v_pk_mul_f32 v[74:75], v[74:75], v[108:109] op_sel_hi:[1,0]
	v_pk_mul_f32 v[72:73], v[72:73], v[108:109] op_sel_hi:[1,0]
	v_pk_mul_f32 v[70:71], v[70:71], v[108:109] op_sel_hi:[1,0]
	v_pk_mul_f32 v[68:69], v[68:69], v[108:109] op_sel_hi:[1,0]
	v_pk_mul_f32 v[66:67], v[66:67], v[108:109] op_sel_hi:[1,0]
	v_mul_f32_e32 v106, v106, v108

.LBB0_694:
	s_add_i32 s82, s82, 1
	s_and_b32 s98, s82, 1
	s_mul_i32 s98, s98, 0x4400
	v_add_u32_e32 v186, s98, v194
	ds_read_b128 v[98:101], v186
	ds_read_b128 v[200:203], v186 offset:32
	ds_read_b128 v[204:207], v186 offset:8704
	ds_read_b128 v[208:211], v186 offset:8736
	s_cmp_lt_u32 s82, s79
	s_cselect_b64 s[76:77], -1, 0
	s_cmp_ge_u32 s82, s79
	s_cbranch_scc1 .LBB0_696
	v_lshl_add_u64 v[82:83], v[184:185], 0, s[72:73]
	v_add_co_u32_e32 v84, vcc, 0xc92b000, v82
	s_nop 1
	v_addc_co_u32_e32 v85, vcc, 0, v83, vcc
	v_add_co_u32_e32 v82, vcc, 0xc92d000, v82
	s_nop 1
	v_addc_co_u32_e32 v83, vcc, 0, v83, vcc
	global_load_dwordx4 v[146:149], v[84:85], off offset:1024
	global_load_dwordx4 v[150:153], v[82:83], off offset:1024
.LBB0_696:
	s_add_i32 s83, s86, s72
	s_and_b32 s1, s82, 1
	s_addk_i32 s83, 0xc000
	s_add_u32 s84, s97, s83
	s_addc_u32 s85, s90, 0
	v_lshl_add_u64 v[82:83], s[84:85], 0, v[178:179]
	v_add_co_u32_e32 v84, vcc, s92, v82
	s_mul_i32 s83, s1, 0x4400
	s_nop 0
	v_addc_co_u32_e32 v85, vcc, 0, v83, vcc
	global_load_dwordx4 v[166:169], v[82:83], off
	global_load_dwordx4 v[170:173], v[84:85], off
	s_waitcnt lgkmcnt(3)
	v_mfma_f32_32x32x16_bf16 v[82:97], v[98:101], v[114:117], v[66:81]
	v_mov_b64_e32 v[112:113], v[80:81]
	v_mov_b64_e32 v[110:111], v[78:79]
	v_mov_b64_e32 v[108:109], v[76:77]
	v_mov_b64_e32 v[106:107], v[74:75]
	v_mov_b64_e32 v[104:105], v[72:73]
	v_mov_b64_e32 v[102:103], v[70:71]
	v_mov_b64_e32 v[100:101], v[68:69]
	v_mov_b64_e32 v[98:99], v[66:67]
	s_waitcnt lgkmcnt(2)
	v_mfma_f32_32x32x16_bf16 v[82:97], v[200:203], v[118:121], v[82:97]
	s_waitcnt lgkmcnt(1)
	v_mfma_f32_32x32x16_bf16 v[98:113], v[204:207], v[114:117], v[98:113]
	ds_read_b128 v[200:203], v186 offset:64
	ds_read_b128 v[204:207], v186 offset:96
	ds_read_b128 v[212:215], v186 offset:8768
	ds_read_b128 v[216:219], v186 offset:8800
	s_waitcnt lgkmcnt(4)
	v_mfma_f32_32x32x16_bf16 v[98:113], v[208:211], v[118:121], v[98:113]
	s_waitcnt lgkmcnt(3)
	v_mfma_f32_32x32x16_bf16 v[82:97], v[200:203], v[122:125], v[82:97]
	s_waitcnt lgkmcnt(1)
	v_mfma_f32_32x32x16_bf16 v[98:113], v[212:215], v[122:125], v[98:113]
	v_mfma_f32_32x32x16_bf16 v[82:97], v[204:207], v[126:129], v[82:97]
	ds_read_b128 v[200:203], v186 offset:128
	ds_read_b128 v[204:207], v186 offset:160
	ds_read_b128 v[208:211], v186 offset:8832
	ds_read_b128 v[212:215], v186 offset:8864
	s_waitcnt lgkmcnt(4)
	v_mfma_f32_32x32x16_bf16 v[98:113], v[216:219], v[126:129], v[98:113]
	s_waitcnt lgkmcnt(3)
	v_mfma_f32_32x32x16_bf16 v[82:97], v[200:203], v[130:133], v[82:97]
	s_waitcnt lgkmcnt(1)
	v_mfma_f32_32x32x16_bf16 v[98:113], v[208:211], v[130:133], v[98:113]
	v_mfma_f32_32x32x16_bf16 v[82:97], v[204:207], v[134:137], v[82:97]
	ds_read_b128 v[200:203], v186 offset:192
	ds_read_b128 v[204:207], v186 offset:224
	ds_read_b128 v[208:211], v186 offset:8896
	ds_read_b128 v[216:219], v186 offset:8928
	s_waitcnt lgkmcnt(4)
	v_mfma_f32_32x32x16_bf16 v[98:113], v[212:215], v[134:137], v[98:113]
	s_waitcnt lgkmcnt(3)
	v_mfma_f32_32x32x16_bf16 v[82:97], v[200:203], v[138:141], v[82:97]
	s_waitcnt lgkmcnt(1)
	v_mfma_f32_32x32x16_bf16 v[98:113], v[208:211], v[138:141], v[98:113]
	v_mfma_f32_32x32x16_bf16 v[82:97], v[204:207], v[142:145], v[82:97]
	s_waitcnt lgkmcnt(0)
	v_mfma_f32_32x32x16_bf16 v[98:113], v[216:219], v[142:145], v[98:113]
	s_cmp_lg_u32 s72, 0xfffe4000
	s_cbranch_scc1 .LBB0_698
	s_nop 7
	v_cndmask_b32_e64 v82, v188, v82, s[6:7]
	s_nop 0
	v_cndmask_b32_e64 v98, v188, v98, s[8:9]
	v_cndmask_b32_e64 v83, v83, v188, s[10:11]
	v_cndmask_b32_e64 v99, v188, v99, s[12:13]
	v_cndmask_b32_e64 v84, v188, v84, s[14:15]
	v_cndmask_b32_e64 v100, v188, v100, s[16:17]
	v_cndmask_b32_e64 v85, v188, v85, s[18:19]
	v_cndmask_b32_e64 v101, v188, v101, s[20:21]
	v_cndmask_b32_e64 v86, v188, v86, s[22:23]
	v_cndmask_b32_e64 v102, v188, v102, s[24:25]
	v_cndmask_b32_e64 v87, v188, v87, s[26:27]
	v_cndmask_b32_e64 v103, v188, v103, s[28:29]
	v_cndmask_b32_e64 v88, v188, v88, s[30:31]
	v_cndmask_b32_e64 v104, v188, v104, s[34:35]
	v_cndmask_b32_e64 v89, v188, v89, s[36:37]
	v_cndmask_b32_e64 v105, v188, v105, s[38:39]
	v_cndmask_b32_e64 v90, v188, v90, s[40:41]
	v_cndmask_b32_e64 v106, v188, v106, s[42:43]
	v_cndmask_b32_e64 v91, v188, v91, s[44:45]
	v_cndmask_b32_e64 v107, v188, v107, s[46:47]
	v_cndmask_b32_e64 v92, v188, v92, s[48:49]
	v_cndmask_b32_e64 v108, v188, v108, s[50:51]
	v_cndmask_b32_e64 v93, v188, v93, s[52:53]
	v_cndmask_b32_e64 v109, v188, v109, s[54:55]
	v_cndmask_b32_e64 v94, v188, v94, s[56:57]
	v_cndmask_b32_e64 v110, v188, v110, s[58:59]
	v_cndmask_b32_e64 v95, v188, v95, s[60:61]
	v_cndmask_b32_e64 v111, v188, v111, s[62:63]
	v_cndmask_b32_e64 v96, v188, v96, s[64:65]
	v_cndmask_b32_e64 v112, v188, v112, s[66:67]
	v_cndmask_b32_e64 v97, v188, v97, s[68:69]
	v_cndmask_b32_e64 v113, v188, v113, s[70:71]

	.amdhsa_kernel _Z14nsa_hybrid_fwd4Args
		.amdhsa_group_segment_fixed_size 0
		.amdhsa_private_segment_fixed_size 0
		.amdhsa_kernarg_size 416
		.amdhsa_user_sgpr_count 2
		.amdhsa_user_sgpr_dispatch_ptr 0
		.amdhsa_user_sgpr_queue_ptr 0
		.amdhsa_user_sgpr_kernarg_segment_ptr 1
		.amdhsa_user_sgpr_dispatch_id 0
		.amdhsa_user_sgpr_kernarg_preload_length 0
		.amdhsa_user_sgpr_kernarg_preload_offset 0
		.amdhsa_user_sgpr_private_segment_size 0
		.amdhsa_uses_dynamic_stack 0
		.amdhsa_enable_private_segment 0
		.amdhsa_system_sgpr_workgroup_id_x 1
		.amdhsa_system_sgpr_workgroup_id_y 0
		.amdhsa_system_sgpr_workgroup_id_z 0
		.amdhsa_system_sgpr_workgroup_info 0
		.amdhsa_system_vgpr_workitem_id 0
		.amdhsa_next_free_vgpr 247
		.amdhsa_next_free_sgpr 102
		.amdhsa_accum_offset 248
		.amdhsa_reserve_vcc 1
		.amdhsa_float_round_mode_32 0
		.amdhsa_float_round_mode_16_64 0
		.amdhsa_float_denorm_mode_32 3
		.amdhsa_float_denorm_mode_16_64 3
		.amdhsa_dx10_clamp 1
		.amdhsa_ieee_mode 1
		.amdhsa_fp16_overflow 0
		.amdhsa_tg_split 0
		.amdhsa_exception_fp_ieee_invalid_op 0
		.amdhsa_exception_fp_denorm_src 0
		.amdhsa_exception_fp_ieee_div_zero 0
		.amdhsa_exception_fp_ieee_overflow 0
		.amdhsa_exception_fp_ieee_underflow 0
		.amdhsa_exception_fp_ieee_inexact 0
		.amdhsa_exception_int_div_zero 0
	.end_amdhsa_kernel

amdhsa.kernels:
  - .agpr_count:     0
    .args:
      - .offset:         0
        .size:           160
        .value_kind:     by_value
      - .offset:         160
        .size:           4
        .value_kind:     hidden_block_count_x
      - .offset:         164
        .size:           4
        .value_kind:     hidden_block_count_y
      - .offset:         168
        .size:           4
        .value_kind:     hidden_block_count_z
      - .offset:         172
        .size:           2
        .value_kind:     hidden_group_size_x
      - .offset:         174
        .size:           2
        .value_kind:     hidden_group_size_y
      - .offset:         176
        .size:           2
        .value_kind:     hidden_group_size_z
      - .offset:         178
        .size:           2
        .value_kind:     hidden_remainder_x
      - .offset:         180
        .size:           2
        .value_kind:     hidden_remainder_y
      - .offset:         182
        .size:           2
        .value_kind:     hidden_remainder_z
      - .offset:         200
        .size:           8
        .value_kind:     hidden_global_offset_x
      - .offset:         208
        .size:           8
        .value_kind:     hidden_global_offset_y
      - .offset:         216
        .size:           8
        .value_kind:     hidden_global_offset_z
      - .offset:         224
        .size:           2
        .value_kind:     hidden_grid_dims
      - .offset:         280
        .size:           4
        .value_kind:     hidden_dynamic_lds_size
    .group_segment_fixed_size: 0
    .kernarg_segment_align: 8
    .kernarg_segment_size: 416
    .language:       OpenCL C
    .language_version:
      - 2
      - 0
    .max_flat_workgroup_size: 512
    .name:           _Z14nsa_hybrid_fwd4Args
    .private_segment_fixed_size: 0
    .sgpr_count:     108
    .sgpr_spill_count: 58
    .symbol:         _Z14nsa_hybrid_fwd4Args.kd
    .uniform_work_group_size: 1
    .uses_dynamic_stack: false
    .vgpr_count:     247
    .vgpr_spill_count: 0
    .wavefront_size: 64
